# same scalar-base addressing for the P6, P8, P11, P15 and P17 GEMM k-loops (8 row offsets, two SGPR bases, four scalar adds per iteration)
# speedup vs baseline: 1.0158x; 1.0063x over previous
.LBB0_1721:
	s_or_b64 exec, exec, s[20:21]
	v_add_u32_e32 v4, s35, v158
	v_ashrrev_i32_e32 v5, 31, v4
	v_lshlrev_b64 v[4:5], 11, v[4:5]
	v_lshl_add_u64 v[140:141], s[82:83], 0, v[4:5]
	v_add_u32_e32 v4, s35, v159
	v_ashrrev_i32_e32 v5, 31, v4
	v_lshlrev_b64 v[4:5], 11, v[4:5]
	v_lshl_add_u64 v[144:145], s[82:83], 0, v[4:5]
	v_add_u32_e32 v4, s35, v160
	v_ashrrev_i32_e32 v5, 31, v4
	v_lshlrev_b64 v[4:5], 11, v[4:5]
	v_lshl_add_u64 v[148:149], s[82:83], 0, v[4:5]
	v_add_u32_e32 v4, s35, v1
	v_ashrrev_i32_e32 v5, 31, v4
	v_lshlrev_b64 v[4:5], 11, v[4:5]
	v_lshl_add_u64 v[138:139], s[82:83], 0, v[48:49]
	v_lshl_add_u64 v[142:143], s[82:83], 0, v[42:43]
	v_lshl_add_u64 v[146:147], s[82:83], 0, v[36:37]
	v_lshl_add_u64 v[150:151], s[82:83], 0, v[34:35]
	v_lshl_add_u64 v[152:153], s[82:83], 0, v[4:5]
	s_mov_b32 s37, 0
	v_mov_b32_e32 v3, v2
	v_mov_b32_e32 v4, v2
	v_mov_b32_e32 v5, v2
	v_mov_b32_e32 v6, v2
	v_mov_b32_e32 v7, v2
	v_mov_b32_e32 v8, v2
	v_mov_b32_e32 v9, v2
	v_mov_b32_e32 v10, v2
	v_mov_b32_e32 v11, v2
	v_mov_b32_e32 v12, v2
	v_mov_b32_e32 v13, v2
	v_mov_b32_e32 v14, v2
	v_mov_b32_e32 v15, v2
	v_mov_b32_e32 v16, v2
	v_mov_b32_e32 v17, v2
	v_mov_b32_e32 v18, v2
	v_mov_b32_e32 v19, v2
	v_mov_b32_e32 v20, v2
	v_mov_b32_e32 v21, v2
	v_mov_b32_e32 v22, v2
	v_mov_b32_e32 v23, v2
	v_mov_b32_e32 v24, v2
	v_mov_b32_e32 v25, v2
	v_mov_b32_e32 v26, v2
	v_mov_b32_e32 v27, v2
	v_mov_b32_e32 v28, v2
	v_mov_b32_e32 v29, v2
	v_mov_b32_e32 v30, v2
	v_mov_b32_e32 v31, v2
	v_mov_b32_e32 v32, v2
	v_mov_b32_e32 v33, v2
	v_mov_b32_e32 v34, v2
	v_mov_b32_e32 v35, v2
	v_mov_b32_e32 v36, v2
	v_mov_b32_e32 v37, v2
	v_mov_b32_e32 v38, v2
	v_mov_b32_e32 v39, v2
	v_mov_b32_e32 v40, v2
	v_mov_b32_e32 v41, v2
	v_mov_b32_e32 v42, v2
	v_mov_b32_e32 v43, v2
	v_mov_b32_e32 v44, v2
	v_mov_b32_e32 v45, v2
	v_mov_b32_e32 v46, v2
	v_mov_b32_e32 v47, v2
	v_mov_b32_e32 v48, v2
	v_mov_b32_e32 v49, v2
	v_mov_b32_e32 v50, v2
	v_mov_b32_e32 v51, v2
	v_mov_b32_e32 v52, v2
	v_mov_b32_e32 v53, v2
	v_mov_b32_e32 v54, v2
	v_mov_b32_e32 v55, v2
	v_mov_b32_e32 v56, v2
	v_mov_b32_e32 v57, v2
	v_mov_b32_e32 v58, v2
	v_mov_b32_e32 v59, v2
	v_mov_b32_e32 v60, v2
	v_mov_b32_e32 v61, v2
	v_mov_b32_e32 v62, v2
	v_mov_b32_e32 v63, v2
	v_mov_b32_e32 v64, v2
	v_mov_b32_e32 v65, v2
	s_waitcnt lgkmcnt(0)
	s_barrier
	ds_read_b128 v[192:195], v161 offset:0
	ds_read_b128 v[196:199], v162 offset:18432
	ds_read_b128 v[200:203], v162 offset:23040
	ds_read_b128 v[204:207], v161 offset:4608
	ds_read_b128 v[208:211], v161 offset:32
	ds_read_b128 v[212:215], v162 offset:18464
	ds_read_b128 v[216:219], v162 offset:23072
	ds_read_b128 v[220:223], v161 offset:4640
	v_subrev_u32_e32 v152, s82, v152
	v_add_u32_e32 v152, v152, v136
	v_subrev_u32_e32 v150, s82, v150
	v_add_u32_e32 v150, v150, v136
	v_subrev_u32_e32 v148, s82, v148
	v_add_u32_e32 v148, v148, v136
	v_subrev_u32_e32 v146, s82, v146
	v_add_u32_e32 v146, v146, v136
	v_subrev_u32_e32 v144, s82, v144
	v_add_u32_e32 v144, v144, v136
	v_subrev_u32_e32 v142, s82, v142
	v_add_u32_e32 v142, v142, v136
	v_subrev_u32_e32 v140, s82, v140
	v_add_u32_e32 v140, v140, v136
	v_subrev_u32_e32 v138, s82, v138
	v_add_u32_e32 v138, v138, v136
	s_add_u32 s84, s82, 0xa380000
	s_addc_u32 s85, s83, 0
	s_add_u32 s86, s82, 0x89c0000
	s_addc_u32 s87, s83, 0
	s_branch .LBB0_1724

.LBB0_1723:
	s_add_i32 s37, s37, 2
	s_add_u32 s84, s84, s18
	s_addc_u32 s85, s85, s19
	s_add_u32 s86, s86, s18
	s_addc_u32 s87, s87, s19
	s_andn2_b64 vcc, exec, s[20:21]
	s_waitcnt lgkmcnt(4)
	v_mfma_f32_32x32x16_bf16 v[50:65], v[192:195], v[196:199], v[50:65]
	v_mfma_f32_32x32x16_bf16 v[34:49], v[192:195], v[200:203], v[34:49]
	v_mfma_f32_32x32x16_bf16 v[18:33], v[204:207], v[196:199], v[18:33]
	v_mfma_f32_32x32x16_bf16 v[2:17], v[204:207], v[200:203], v[2:17]
	ds_read_b128 v[164:167], v161 offset:36928
	ds_read_b128 v[168:171], v162 offset:55360
	ds_read_b128 v[172:175], v162 offset:59968
	ds_read_b128 v[176:179], v161 offset:41536
	s_waitcnt lgkmcnt(4)
	v_mfma_f32_32x32x16_bf16 v[50:65], v[208:211], v[212:215], v[50:65]
	v_mfma_f32_32x32x16_bf16 v[34:49], v[208:211], v[216:219], v[34:49]
	v_mfma_f32_32x32x16_bf16 v[18:33], v[220:223], v[212:215], v[18:33]
	v_mfma_f32_32x32x16_bf16 v[2:17], v[220:223], v[216:219], v[2:17]
	ds_read_b128 v[180:183], v161 offset:36960
	ds_read_b128 v[184:187], v162 offset:55392
	ds_read_b128 v[188:191], v162 offset:60000
	ds_read_b128 v[224:227], v161 offset:41568
	s_waitcnt lgkmcnt(4)
	v_mfma_f32_32x32x16_bf16 v[50:65], v[164:167], v[168:171], v[50:65]
	v_mfma_f32_32x32x16_bf16 v[34:49], v[164:167], v[172:175], v[34:49]
	s_waitcnt lgkmcnt(0)
	s_barrier
	ds_read_b128 v[192:195], v161 offset:0
	ds_read_b128 v[196:199], v162 offset:18432
	ds_read_b128 v[200:203], v162 offset:23040
	ds_read_b128 v[204:207], v161 offset:4608
	ds_read_b128 v[208:211], v161 offset:32
	ds_read_b128 v[212:215], v162 offset:18464
	ds_read_b128 v[216:219], v162 offset:23072
	ds_read_b128 v[220:223], v161 offset:4640
	v_mfma_f32_32x32x16_bf16 v[18:33], v[176:179], v[168:171], v[18:33]
	v_mfma_f32_32x32x16_bf16 v[2:17], v[176:179], v[172:175], v[2:17]
	v_mfma_f32_32x32x16_bf16 v[50:65], v[180:183], v[184:187], v[50:65]
	v_mfma_f32_32x32x16_bf16 v[34:49], v[180:183], v[188:191], v[34:49]
	v_mfma_f32_32x32x16_bf16 v[18:33], v[224:227], v[184:187], v[18:33]
	v_mfma_f32_32x32x16_bf16 v[2:17], v[224:227], v[188:191], v[2:17]
	s_cbranch_vccz .LBB0_1682
.LBB0_1724:
	s_cmp_gt_u32 s37, 12
	s_waitcnt vmcnt(3)
	ds_write_b128 v154, v[66:69] offset:36864
	ds_write_b128 v154, v[70:73] offset:55296
	s_waitcnt vmcnt(2)
	ds_write_b128 v154, v[78:81] offset:41472
	ds_write_b128 v154, v[74:77] offset:59904
	s_waitcnt vmcnt(1)
	ds_write_b128 v154, v[82:85] offset:46080
	ds_write_b128 v154, v[90:93] offset:64512
	s_waitcnt vmcnt(0)
	ds_write_b128 v154, v[102:105] offset:50688
	ds_write_b128 v156, v[106:109] offset:13824
	s_cbranch_scc1 .LBB0_1734
	v_mov_b32_e32 v76, 0
	s_nop 0
	global_load_dwordx4 v[66:69], v152, s[84:85] offset:384
	v_mov_b32_e32 v77, v130
	v_mov_b64_e32 v[72:73], v[76:77]
	v_mov_b64_e32 v[70:71], v[76:77]
	s_and_saveexec_b64 s[20:21], s[4:5]
	s_cbranch_execz .LBB0_1727
	s_nop 1
	global_load_dwordx4 v[70:73], v150, s[86:87] offset:384
.LBB0_1727:
	s_or_b64 exec, exec, s[20:21]
	s_nop 1
	global_load_dwordx4 v[78:81], v148, s[84:85] offset:384
	v_mov_b64_e32 v[74:75], v[76:77]
	s_and_saveexec_b64 s[20:21], s[6:7]
	s_cbranch_execz .LBB0_1729
	s_nop 1
	global_load_dwordx4 v[74:77], v146, s[86:87] offset:384
.LBB0_1729:
	s_or_b64 exec, exec, s[20:21]
	v_mov_b32_e32 v131, v130
	s_nop 0
	global_load_dwordx4 v[82:85], v144, s[84:85] offset:384
	v_mov_b64_e32 v[92:93], v[130:131]
	v_mov_b64_e32 v[90:91], v[130:131]
	s_and_saveexec_b64 s[20:21], s[8:9]
	s_cbranch_execz .LBB0_1731
	s_nop 1
	global_load_dwordx4 v[90:93], v142, s[86:87] offset:384
.LBB0_1731:
	s_or_b64 exec, exec, s[20:21]
	v_mov_b32_e32 v107, 0
	s_nop 0
	global_load_dwordx4 v[102:105], v140, s[84:85] offset:384
	v_mov_b32_e32 v106, 0
	v_mov_b32_e32 v109, 0
	v_mov_b32_e32 v108, 0
	s_and_saveexec_b64 s[20:21], s[10:11]
	s_cbranch_execz .LBB0_1733
	s_nop 1
	global_load_dwordx4 v[106:109], v138, s[86:87] offset:384

.LBB0_1734:
	s_cmp_gt_u32 s37, 13
	s_cselect_b64 s[20:21], -1, 0
	s_and_b64 vcc, exec, s[20:21]
	s_waitcnt lgkmcnt(4)
	v_mfma_f32_32x32x16_bf16 v[50:65], v[192:195], v[196:199], v[50:65]
	v_mfma_f32_32x32x16_bf16 v[34:49], v[192:195], v[200:203], v[34:49]
	v_mfma_f32_32x32x16_bf16 v[18:33], v[204:207], v[196:199], v[18:33]
	v_mfma_f32_32x32x16_bf16 v[2:17], v[204:207], v[200:203], v[2:17]
	ds_read_b128 v[164:167], v161 offset:64
	ds_read_b128 v[168:171], v162 offset:18496
	ds_read_b128 v[172:175], v162 offset:23104
	ds_read_b128 v[176:179], v161 offset:4672
	s_waitcnt lgkmcnt(4)
	v_mfma_f32_32x32x16_bf16 v[50:65], v[208:211], v[212:215], v[50:65]
	v_mfma_f32_32x32x16_bf16 v[34:49], v[208:211], v[216:219], v[34:49]
	v_mfma_f32_32x32x16_bf16 v[18:33], v[220:223], v[212:215], v[18:33]
	v_mfma_f32_32x32x16_bf16 v[2:17], v[220:223], v[216:219], v[2:17]
	ds_read_b128 v[180:183], v161 offset:96
	ds_read_b128 v[184:187], v162 offset:18528
	ds_read_b128 v[188:191], v162 offset:23136
	ds_read_b128 v[224:227], v161 offset:4704
	s_waitcnt lgkmcnt(4)
	v_mfma_f32_32x32x16_bf16 v[50:65], v[164:167], v[168:171], v[50:65]
	v_mfma_f32_32x32x16_bf16 v[34:49], v[164:167], v[172:175], v[34:49]
	s_waitcnt lgkmcnt(0)
	s_barrier
	ds_read_b128 v[192:195], v161 offset:36864
	ds_read_b128 v[196:199], v162 offset:55296
	ds_read_b128 v[200:203], v162 offset:59904
	ds_read_b128 v[204:207], v161 offset:41472
	ds_read_b128 v[208:211], v161 offset:36896
	ds_read_b128 v[212:215], v162 offset:55328
	ds_read_b128 v[216:219], v162 offset:59936
	ds_read_b128 v[220:223], v161 offset:41504
	v_mfma_f32_32x32x16_bf16 v[18:33], v[176:179], v[168:171], v[18:33]
	v_mfma_f32_32x32x16_bf16 v[2:17], v[176:179], v[172:175], v[2:17]
	v_mfma_f32_32x32x16_bf16 v[50:65], v[180:183], v[184:187], v[50:65]
	v_mfma_f32_32x32x16_bf16 v[34:49], v[180:183], v[188:191], v[34:49]
	v_mfma_f32_32x32x16_bf16 v[18:33], v[224:227], v[184:187], v[18:33]
	v_mfma_f32_32x32x16_bf16 v[2:17], v[224:227], v[188:191], v[2:17]
	s_cbranch_vccnz .LBB0_1723
	s_cmp_gt_u32 s37, 11
	s_waitcnt vmcnt(3)
	ds_write_b128 v154, v[86:89]
	ds_write_b128 v154, v[94:97] offset:18432
	s_waitcnt vmcnt(2)
	ds_write_b128 v154, v[110:113] offset:4608
	ds_write_b128 v154, v[98:101] offset:23040
	s_waitcnt vmcnt(1)
	ds_write_b128 v154, v[114:117] offset:9216
	ds_write_b128 v154, v[118:121] offset:27648
	s_waitcnt vmcnt(0)
	ds_write_b128 v154, v[122:125] offset:13824
	ds_write_b128 v154, v[126:129] offset:32256
	s_cbranch_scc1 .LBB0_1723
	v_mov_b32_e32 v100, 0
	s_nop 0
	global_load_dwordx4 v[86:89], v152, s[84:85] offset:512
	v_mov_b32_e32 v101, v130
	v_mov_b64_e32 v[96:97], v[100:101]
	v_mov_b64_e32 v[94:95], v[100:101]
	s_and_saveexec_b64 s[22:23], s[4:5]
	s_cbranch_execz .LBB0_1738
	s_nop 1
	global_load_dwordx4 v[94:97], v150, s[86:87] offset:512
.LBB0_1738:
	s_or_b64 exec, exec, s[22:23]
	s_nop 1
	global_load_dwordx4 v[110:113], v148, s[84:85] offset:512
	v_mov_b64_e32 v[98:99], v[100:101]
	s_and_saveexec_b64 s[22:23], s[6:7]
	s_cbranch_execz .LBB0_1740
	s_nop 1
	global_load_dwordx4 v[98:101], v146, s[86:87] offset:512
.LBB0_1740:
	s_or_b64 exec, exec, s[22:23]
	v_mov_b32_e32 v131, v130
	s_nop 0
	global_load_dwordx4 v[114:117], v144, s[84:85] offset:512
	v_mov_b64_e32 v[120:121], v[130:131]
	v_mov_b64_e32 v[118:119], v[130:131]
	s_and_saveexec_b64 s[22:23], s[8:9]
	s_cbranch_execz .LBB0_1742
	s_nop 1
	global_load_dwordx4 v[118:121], v142, s[86:87] offset:512
.LBB0_1742:
	s_or_b64 exec, exec, s[22:23]
	v_mov_b32_e32 v127, 0
	s_nop 0
	global_load_dwordx4 v[122:125], v140, s[84:85] offset:512
	v_mov_b32_e32 v126, 0
	v_mov_b32_e32 v129, 0
	v_mov_b32_e32 v128, 0
	s_and_saveexec_b64 s[22:23], s[10:11]
	s_cbranch_execz .LBB0_1722
	s_nop 1
	global_load_dwordx4 v[126:129], v138, s[86:87] offset:512
	s_branch .LBB0_1722

.LBB0_1920:
	s_or_b64 exec, exec, s[2:3]
	v_add_u32_e32 v2, s33, v194
	v_ashrrev_i32_e32 v3, 31, v2
	v_lshlrev_b64 v[2:3], 11, v[2:3]
	v_lshl_add_u64 v[168:169], s[82:83], 0, v[2:3]
	v_add_u32_e32 v2, s33, v195
	v_ashrrev_i32_e32 v3, 31, v2
	v_lshlrev_b64 v[2:3], 11, v[2:3]
	v_lshl_add_u64 v[172:173], s[82:83], 0, v[2:3]
	v_add_u32_e32 v2, s33, v196
	v_ashrrev_i32_e32 v3, 31, v2
	v_lshlrev_b64 v[2:3], 11, v[2:3]
	v_lshl_add_u64 v[176:177], s[82:83], 0, v[2:3]
	v_add_u32_e32 v2, s33, v1
	v_ashrrev_i32_e32 v3, 31, v2
	v_lshlrev_b64 v[2:3], 11, v[2:3]
	v_lshl_add_u64 v[166:167], s[82:83], 0, v[48:49]
	v_lshl_add_u64 v[170:171], s[82:83], 0, v[42:43]
	v_lshl_add_u64 v[174:175], s[82:83], 0, v[36:37]
	v_lshl_add_u64 v[178:179], s[82:83], 0, v[34:35]
	v_lshl_add_u64 v[180:181], s[82:83], 0, v[2:3]
	s_mov_b32 s35, 0
	v_mov_b32_e32 v51, v50
	v_mov_b32_e32 v52, v50
	v_mov_b32_e32 v53, v50
	v_mov_b32_e32 v54, v50
	v_mov_b32_e32 v55, v50
	v_mov_b32_e32 v56, v50
	v_mov_b32_e32 v57, v50
	v_mov_b32_e32 v58, v50
	v_mov_b32_e32 v59, v50
	v_mov_b32_e32 v60, v50
	v_mov_b32_e32 v61, v50
	v_mov_b32_e32 v62, v50
	v_mov_b32_e32 v63, v50
	v_mov_b32_e32 v64, v50
	v_mov_b32_e32 v65, v50
	v_mov_b32_e32 v34, v50
	v_mov_b32_e32 v35, v50
	v_mov_b32_e32 v36, v50
	v_mov_b32_e32 v37, v50
	v_mov_b32_e32 v38, v50
	v_mov_b32_e32 v39, v50
	v_mov_b32_e32 v40, v50
	v_mov_b32_e32 v41, v50
	v_mov_b32_e32 v42, v50
	v_mov_b32_e32 v43, v50
	v_mov_b32_e32 v44, v50
	v_mov_b32_e32 v45, v50
	v_mov_b32_e32 v46, v50
	v_mov_b32_e32 v47, v50
	v_mov_b32_e32 v48, v50
	v_mov_b32_e32 v49, v50
	v_mov_b32_e32 v18, v50
	v_mov_b32_e32 v19, v50
	v_mov_b32_e32 v20, v50
	v_mov_b32_e32 v21, v50
	v_mov_b32_e32 v22, v50
	v_mov_b32_e32 v23, v50
	v_mov_b32_e32 v24, v50
	v_mov_b32_e32 v25, v50
	v_mov_b32_e32 v26, v50
	v_mov_b32_e32 v27, v50
	v_mov_b32_e32 v28, v50
	v_mov_b32_e32 v29, v50
	v_mov_b32_e32 v30, v50
	v_mov_b32_e32 v31, v50
	v_mov_b32_e32 v32, v50
	v_mov_b32_e32 v33, v50
	v_mov_b32_e32 v2, v50
	v_mov_b32_e32 v3, v50
	v_mov_b32_e32 v4, v50
	v_mov_b32_e32 v5, v50
	v_mov_b32_e32 v6, v50
	v_mov_b32_e32 v7, v50
	v_mov_b32_e32 v8, v50
	v_mov_b32_e32 v9, v50
	v_mov_b32_e32 v10, v50
	v_mov_b32_e32 v11, v50
	v_mov_b32_e32 v12, v50
	v_mov_b32_e32 v13, v50
	v_mov_b32_e32 v14, v50
	v_mov_b32_e32 v15, v50
	v_mov_b32_e32 v16, v50
	v_mov_b32_e32 v17, v50
	s_waitcnt lgkmcnt(0)
	s_barrier
	ds_read_b128 v[206:209], v203 offset:0
	ds_read_b128 v[210:213], v204 offset:18432
	ds_read_b128 v[214:217], v204 offset:23040
	ds_read_b128 v[218:221], v203 offset:4608
	ds_read_b128 v[222:225], v203 offset:32
	ds_read_b128 v[226:229], v204 offset:18464
	ds_read_b128 v[230:233], v204 offset:23072
	ds_read_b128 v[234:237], v203 offset:4640
	v_subrev_u32_e32 v180, s82, v180
	v_add_u32_e32 v180, v180, v138
	v_subrev_u32_e32 v178, s82, v178
	v_add_u32_e32 v178, v178, v138
	v_subrev_u32_e32 v176, s82, v176
	v_add_u32_e32 v176, v176, v138
	v_subrev_u32_e32 v174, s82, v174
	v_add_u32_e32 v174, v174, v138
	v_subrev_u32_e32 v172, s82, v172
	v_add_u32_e32 v172, v172, v138
	v_subrev_u32_e32 v170, s82, v170
	v_add_u32_e32 v170, v170, v138
	v_subrev_u32_e32 v168, s82, v168
	v_add_u32_e32 v168, v168, v138
	v_subrev_u32_e32 v166, s82, v166
	v_add_u32_e32 v166, v166, v138
	s_add_u32 s84, s82, 0xc4c0000
	s_addc_u32 s85, s83, 0
	s_add_u32 s86, s82, 0x99d0000
	s_addc_u32 s87, s83, 0
	s_branch .LBB0_1923

.LBB0_1922:
	s_add_i32 s35, s35, 2
	s_add_u32 s84, s84, s30
	s_addc_u32 s85, s85, s31
	s_add_u32 s86, s86, s30
	s_addc_u32 s87, s87, s31
	s_andn2_b64 vcc, exec, s[2:3]
	s_waitcnt lgkmcnt(4)
	v_mfma_f32_32x32x16_bf16 v[50:65], v[206:209], v[210:213], v[50:65]
	v_mfma_f32_32x32x16_bf16 v[34:49], v[206:209], v[214:217], v[34:49]
	v_mfma_f32_32x32x16_bf16 v[18:33], v[218:221], v[210:213], v[18:33]
	v_mfma_f32_32x32x16_bf16 v[2:17], v[218:221], v[214:217], v[2:17]
	ds_read_b128 v[206:209], v203 offset:36928
	ds_read_b128 v[210:213], v204 offset:55360
	ds_read_b128 v[214:217], v204 offset:59968
	ds_read_b128 v[218:221], v203 offset:41536
	s_waitcnt lgkmcnt(4)
	v_mfma_f32_32x32x16_bf16 v[50:65], v[222:225], v[226:229], v[50:65]
	v_mfma_f32_32x32x16_bf16 v[34:49], v[222:225], v[230:233], v[34:49]
	v_mfma_f32_32x32x16_bf16 v[18:33], v[234:237], v[226:229], v[18:33]
	v_mfma_f32_32x32x16_bf16 v[2:17], v[234:237], v[230:233], v[2:17]
	ds_read_b128 v[222:225], v203 offset:36960
	ds_read_b128 v[226:229], v204 offset:55392
	ds_read_b128 v[230:233], v204 offset:60000
	ds_read_b128 v[234:237], v203 offset:41568
	s_waitcnt lgkmcnt(4)
	v_mfma_f32_32x32x16_bf16 v[50:65], v[206:209], v[210:213], v[50:65]
	v_mfma_f32_32x32x16_bf16 v[34:49], v[206:209], v[214:217], v[34:49]
	s_waitcnt lgkmcnt(0)
	s_barrier
	v_mfma_f32_32x32x16_bf16 v[18:33], v[218:221], v[210:213], v[18:33]
	v_mfma_f32_32x32x16_bf16 v[2:17], v[218:221], v[214:217], v[2:17]
	ds_read_b128 v[206:209], v203 offset:0
	ds_read_b128 v[210:213], v204 offset:18432
	ds_read_b128 v[214:217], v204 offset:23040
	ds_read_b128 v[218:221], v203 offset:4608
	v_mfma_f32_32x32x16_bf16 v[50:65], v[222:225], v[226:229], v[50:65]
	v_mfma_f32_32x32x16_bf16 v[34:49], v[222:225], v[230:233], v[34:49]
	v_mfma_f32_32x32x16_bf16 v[18:33], v[234:237], v[226:229], v[18:33]
	v_mfma_f32_32x32x16_bf16 v[2:17], v[234:237], v[230:233], v[2:17]
	ds_read_b128 v[222:225], v203 offset:32
	ds_read_b128 v[226:229], v204 offset:18464
	ds_read_b128 v[230:233], v204 offset:23072
	ds_read_b128 v[234:237], v203 offset:4640
	s_cbranch_vccz .LBB0_1943
.LBB0_1923:
	s_cmp_gt_u32 s35, 12
	s_waitcnt vmcnt(3)
	ds_write_b128 v137, v[66:69] offset:36864
	ds_write_b128 v137, v[70:73] offset:55296
	s_waitcnt vmcnt(2)
	ds_write_b128 v137, v[78:81] offset:41472
	ds_write_b128 v137, v[74:77] offset:59904
	s_waitcnt vmcnt(1)
	ds_write_b128 v137, v[82:85] offset:46080
	ds_write_b128 v137, v[90:93] offset:64512
	s_waitcnt vmcnt(0)
	ds_write_b128 v137, v[102:105] offset:50688
	ds_write_b128 v183, v[106:109] offset:13824
	s_cbranch_scc1 .LBB0_1933
	v_mov_b32_e32 v76, 0
	s_nop 0
	global_load_dwordx4 v[66:69], v180, s[84:85] offset:384
	v_mov_b32_e32 v77, v130
	v_mov_b64_e32 v[72:73], v[76:77]
	v_mov_b64_e32 v[70:71], v[76:77]
	s_and_saveexec_b64 s[2:3], s[12:13]
	s_cbranch_execz .LBB0_1926
	s_nop 1
	global_load_dwordx4 v[70:73], v178, s[86:87] offset:384
.LBB0_1926:
	s_or_b64 exec, exec, s[2:3]
	s_nop 1
	global_load_dwordx4 v[78:81], v176, s[84:85] offset:384
	v_mov_b64_e32 v[74:75], v[76:77]
	s_and_saveexec_b64 s[2:3], s[14:15]
	s_cbranch_execz .LBB0_1928
	s_nop 1
	global_load_dwordx4 v[74:77], v174, s[86:87] offset:384
.LBB0_1928:
	s_or_b64 exec, exec, s[2:3]
	v_mov_b32_e32 v131, v130
	s_nop 0
	global_load_dwordx4 v[82:85], v172, s[84:85] offset:384
	v_mov_b64_e32 v[92:93], v[130:131]
	v_mov_b64_e32 v[90:91], v[130:131]
	s_and_saveexec_b64 s[2:3], s[16:17]
	s_cbranch_execz .LBB0_1930
	s_nop 1
	global_load_dwordx4 v[90:93], v170, s[86:87] offset:384
.LBB0_1930:
	s_or_b64 exec, exec, s[2:3]
	v_mov_b32_e32 v107, 0
	s_nop 0
	global_load_dwordx4 v[102:105], v168, s[84:85] offset:384
	v_mov_b32_e32 v106, 0
	v_mov_b32_e32 v109, 0
	v_mov_b32_e32 v108, 0
	s_and_saveexec_b64 s[2:3], s[18:19]
	s_cbranch_execz .LBB0_1932
	s_nop 1
	global_load_dwordx4 v[106:109], v166, s[86:87] offset:384

.LBB0_1933:
	s_cmp_gt_u32 s35, 13
	s_cselect_b64 s[2:3], -1, 0
	s_and_b64 vcc, exec, s[2:3]
	s_waitcnt lgkmcnt(4)
	v_mfma_f32_32x32x16_bf16 v[50:65], v[206:209], v[210:213], v[50:65]
	v_mfma_f32_32x32x16_bf16 v[34:49], v[206:209], v[214:217], v[34:49]
	v_mfma_f32_32x32x16_bf16 v[18:33], v[218:221], v[210:213], v[18:33]
	v_mfma_f32_32x32x16_bf16 v[2:17], v[218:221], v[214:217], v[2:17]
	ds_read_b128 v[206:209], v203 offset:64
	ds_read_b128 v[210:213], v204 offset:18496
	ds_read_b128 v[214:217], v204 offset:23104
	ds_read_b128 v[218:221], v203 offset:4672
	s_waitcnt lgkmcnt(4)
	v_mfma_f32_32x32x16_bf16 v[50:65], v[222:225], v[226:229], v[50:65]
	v_mfma_f32_32x32x16_bf16 v[34:49], v[222:225], v[230:233], v[34:49]
	v_mfma_f32_32x32x16_bf16 v[18:33], v[234:237], v[226:229], v[18:33]
	v_mfma_f32_32x32x16_bf16 v[2:17], v[234:237], v[230:233], v[2:17]
	ds_read_b128 v[222:225], v203 offset:96
	ds_read_b128 v[226:229], v204 offset:18528
	ds_read_b128 v[230:233], v204 offset:23136
	ds_read_b128 v[234:237], v203 offset:4704
	s_waitcnt lgkmcnt(4)
	v_mfma_f32_32x32x16_bf16 v[50:65], v[206:209], v[210:213], v[50:65]
	v_mfma_f32_32x32x16_bf16 v[34:49], v[206:209], v[214:217], v[34:49]
	s_waitcnt lgkmcnt(0)
	s_barrier
	v_mfma_f32_32x32x16_bf16 v[18:33], v[218:221], v[210:213], v[18:33]
	v_mfma_f32_32x32x16_bf16 v[2:17], v[218:221], v[214:217], v[2:17]
	ds_read_b128 v[206:209], v203 offset:36864
	ds_read_b128 v[210:213], v204 offset:55296
	ds_read_b128 v[214:217], v204 offset:59904
	ds_read_b128 v[218:221], v203 offset:41472
	v_mfma_f32_32x32x16_bf16 v[50:65], v[222:225], v[226:229], v[50:65]
	v_mfma_f32_32x32x16_bf16 v[34:49], v[222:225], v[230:233], v[34:49]
	v_mfma_f32_32x32x16_bf16 v[18:33], v[234:237], v[226:229], v[18:33]
	v_mfma_f32_32x32x16_bf16 v[2:17], v[234:237], v[230:233], v[2:17]
	ds_read_b128 v[222:225], v203 offset:36896
	ds_read_b128 v[226:229], v204 offset:55328
	ds_read_b128 v[230:233], v204 offset:59936
	ds_read_b128 v[234:237], v203 offset:41504
	s_cbranch_vccnz .LBB0_1922
	s_cmp_gt_u32 s35, 11
	s_waitcnt vmcnt(3)
	ds_write_b128 v137, v[86:89]
	ds_write_b128 v137, v[94:97] offset:18432
	s_waitcnt vmcnt(2)
	ds_write_b128 v137, v[110:113] offset:4608
	ds_write_b128 v137, v[98:101] offset:23040
	s_waitcnt vmcnt(1)
	ds_write_b128 v137, v[114:117] offset:9216
	ds_write_b128 v137, v[118:121] offset:27648
	s_waitcnt vmcnt(0)
	ds_write_b128 v137, v[122:125] offset:13824
	ds_write_b128 v137, v[126:129] offset:32256
	s_cbranch_scc1 .LBB0_1922
	v_mov_b32_e32 v100, 0
	s_nop 0
	global_load_dwordx4 v[86:89], v180, s[84:85] offset:512
	v_mov_b32_e32 v101, v130
	v_mov_b64_e32 v[96:97], v[100:101]
	v_mov_b64_e32 v[94:95], v[100:101]
	s_and_saveexec_b64 s[36:37], s[12:13]
	s_cbranch_execz .LBB0_1937
	s_nop 1
	global_load_dwordx4 v[94:97], v178, s[86:87] offset:512
.LBB0_1937:
	s_or_b64 exec, exec, s[36:37]
	s_nop 1
	global_load_dwordx4 v[110:113], v176, s[84:85] offset:512
	v_mov_b64_e32 v[98:99], v[100:101]
	s_and_saveexec_b64 s[36:37], s[14:15]
	s_cbranch_execz .LBB0_1939
	s_nop 1
	global_load_dwordx4 v[98:101], v174, s[86:87] offset:512
.LBB0_1939:
	s_or_b64 exec, exec, s[36:37]
	v_mov_b32_e32 v131, v130
	s_nop 0
	global_load_dwordx4 v[114:117], v172, s[84:85] offset:512
	v_mov_b64_e32 v[120:121], v[130:131]
	v_mov_b64_e32 v[118:119], v[130:131]
	s_and_saveexec_b64 s[36:37], s[16:17]
	s_cbranch_execz .LBB0_1941
	s_nop 1
	global_load_dwordx4 v[118:121], v170, s[86:87] offset:512
.LBB0_1941:
	s_or_b64 exec, exec, s[36:37]
	v_mov_b32_e32 v127, 0
	s_nop 0
	global_load_dwordx4 v[122:125], v168, s[84:85] offset:512
	v_mov_b32_e32 v126, 0
	v_mov_b32_e32 v129, 0
	v_mov_b32_e32 v128, 0
	s_and_saveexec_b64 s[36:37], s[18:19]
	s_cbranch_execz .LBB0_1921
	s_nop 1
	global_load_dwordx4 v[126:129], v166, s[86:87] offset:512
	s_branch .LBB0_1921

.LBB0_2250:
	s_or_b64 exec, exec, s[2:3]
	v_add_u32_e32 v4, s27, v180
	v_ashrrev_i32_e32 v5, 31, v4
	v_lshlrev_b64 v[4:5], 11, v[4:5]
	v_lshl_add_u64 v[146:147], s[82:83], 0, v[4:5]
	v_add_u32_e32 v4, s27, v181
	v_ashrrev_i32_e32 v5, 31, v4
	v_lshlrev_b64 v[4:5], 11, v[4:5]
	v_lshl_add_u64 v[154:155], s[82:83], 0, v[4:5]
	v_add_u32_e32 v4, s26, v1
	v_ashrrev_i32_e32 v5, 31, v4
	v_lshlrev_b64 v[4:5], 11, v[4:5]
	v_lshl_add_u64 v[156:157], s[82:83], 0, v[4:5]
	v_add_u32_e32 v4, s27, v1
	v_ashrrev_i32_e32 v5, 31, v4
	v_lshlrev_b64 v[4:5], 11, v[4:5]
	v_lshl_add_u64 v[144:145], s[82:83], 0, v[40:41]
	v_lshl_add_u64 v[148:149], s[82:83], 0, v[38:39]
	v_lshl_add_u64 v[150:151], s[82:83], 0, v[36:37]
	v_lshl_add_u64 v[152:153], s[82:83], 0, v[34:35]
	v_lshl_add_u64 v[158:159], s[82:83], 0, v[4:5]
	s_mov_b32 s13, 0
	v_mov_b32_e32 v3, v2
	v_mov_b32_e32 v4, v2
	v_mov_b32_e32 v5, v2
	v_mov_b32_e32 v6, v2
	v_mov_b32_e32 v7, v2
	v_mov_b32_e32 v8, v2
	v_mov_b32_e32 v9, v2
	v_mov_b32_e32 v10, v2
	v_mov_b32_e32 v11, v2
	v_mov_b32_e32 v12, v2
	v_mov_b32_e32 v13, v2
	v_mov_b32_e32 v14, v2
	v_mov_b32_e32 v15, v2
	v_mov_b32_e32 v16, v2
	v_mov_b32_e32 v17, v2
	v_mov_b32_e32 v18, v2
	v_mov_b32_e32 v19, v2
	v_mov_b32_e32 v20, v2
	v_mov_b32_e32 v21, v2
	v_mov_b32_e32 v22, v2
	v_mov_b32_e32 v23, v2
	v_mov_b32_e32 v24, v2
	v_mov_b32_e32 v25, v2
	v_mov_b32_e32 v26, v2
	v_mov_b32_e32 v27, v2
	v_mov_b32_e32 v28, v2
	v_mov_b32_e32 v29, v2
	v_mov_b32_e32 v30, v2
	v_mov_b32_e32 v31, v2
	v_mov_b32_e32 v32, v2
	v_mov_b32_e32 v33, v2
	v_mov_b32_e32 v34, v2
	v_mov_b32_e32 v35, v2
	v_mov_b32_e32 v36, v2
	v_mov_b32_e32 v37, v2
	v_mov_b32_e32 v38, v2
	v_mov_b32_e32 v39, v2
	v_mov_b32_e32 v40, v2
	v_mov_b32_e32 v41, v2
	v_mov_b32_e32 v42, v2
	v_mov_b32_e32 v43, v2
	v_mov_b32_e32 v44, v2
	v_mov_b32_e32 v45, v2
	v_mov_b32_e32 v46, v2
	v_mov_b32_e32 v47, v2
	v_mov_b32_e32 v48, v2
	v_mov_b32_e32 v49, v2
	v_mov_b32_e32 v50, v2
	v_mov_b32_e32 v51, v2
	v_mov_b32_e32 v52, v2
	v_mov_b32_e32 v53, v2
	v_mov_b32_e32 v54, v2
	v_mov_b32_e32 v55, v2
	v_mov_b32_e32 v56, v2
	v_mov_b32_e32 v57, v2
	v_mov_b32_e32 v58, v2
	v_mov_b32_e32 v59, v2
	v_mov_b32_e32 v60, v2
	v_mov_b32_e32 v61, v2
	v_mov_b32_e32 v62, v2
	v_mov_b32_e32 v63, v2
	v_mov_b32_e32 v64, v2
	v_mov_b32_e32 v65, v2
	s_waitcnt lgkmcnt(0)
	s_barrier
	ds_read_b128 v[212:215], v182 offset:18432
	ds_read_b128 v[216:219], v162 offset:0
	ds_read_b128 v[220:223], v182 offset:23040
	ds_read_b128 v[224:227], v162 offset:4608
	ds_read_b128 v[228:231], v182 offset:18464
	ds_read_b128 v[232:235], v162 offset:32
	ds_read_b128 v[236:239], v182 offset:23072
	ds_read_b128 v[240:243], v162 offset:4640
	v_subrev_u32_e32 v158, s82, v158
	v_add_u32_e32 v158, v158, v140
	v_subrev_u32_e32 v156, s82, v156
	v_add_u32_e32 v156, v156, v140
	v_subrev_u32_e32 v154, s82, v154
	v_add_u32_e32 v154, v154, v140
	v_subrev_u32_e32 v152, s82, v152
	v_add_u32_e32 v152, v152, v140
	v_subrev_u32_e32 v150, s82, v150
	v_add_u32_e32 v150, v150, v140
	v_subrev_u32_e32 v148, s82, v148
	v_add_u32_e32 v148, v148, v140
	v_subrev_u32_e32 v146, s82, v146
	v_add_u32_e32 v146, v146, v140
	v_subrev_u32_e32 v144, s82, v144
	v_add_u32_e32 v144, v144, v140
	s_add_u32 s84, s82, 0xa380000
	s_addc_u32 s85, s83, 0
	s_add_u32 s86, s82, 0x8bc0000
	s_addc_u32 s87, s83, 0
	s_branch .LBB0_2253

.LBB0_2252:
	s_add_i32 s13, s13, 2
	s_add_u32 s84, s84, s22
	s_addc_u32 s85, s85, s23
	s_add_u32 s86, s86, s22
	s_addc_u32 s87, s87, s23
	s_andn2_b64 vcc, exec, s[2:3]
	s_waitcnt lgkmcnt(4)
	v_mfma_f32_32x32x16_bf16 v[50:65], v[212:215], v[216:219], v[50:65]
	v_mfma_f32_32x32x16_bf16 v[34:49], v[220:223], v[216:219], v[34:49]
	v_mfma_f32_32x32x16_bf16 v[18:33], v[212:215], v[224:227], v[18:33]
	v_mfma_f32_32x32x16_bf16 v[2:17], v[220:223], v[224:227], v[2:17]
	ds_read_b128 v[184:187], v182 offset:55360
	ds_read_b128 v[188:191], v162 offset:36928
	ds_read_b128 v[192:195], v182 offset:59968
	ds_read_b128 v[196:199], v162 offset:41536
	s_waitcnt lgkmcnt(4)
	v_mfma_f32_32x32x16_bf16 v[50:65], v[228:231], v[232:235], v[50:65]
	v_mfma_f32_32x32x16_bf16 v[34:49], v[236:239], v[232:235], v[34:49]
	v_mfma_f32_32x32x16_bf16 v[18:33], v[228:231], v[240:243], v[18:33]
	v_mfma_f32_32x32x16_bf16 v[2:17], v[236:239], v[240:243], v[2:17]
	ds_read_b128 v[200:203], v182 offset:55392
	ds_read_b128 v[204:207], v162 offset:36960
	ds_read_b128 v[208:211], v182 offset:60000
	ds_read_b128 v[248:251], v162 offset:41568
	s_waitcnt lgkmcnt(4)
	v_mfma_f32_32x32x16_bf16 v[50:65], v[184:187], v[188:191], v[50:65]
	v_mfma_f32_32x32x16_bf16 v[34:49], v[192:195], v[188:191], v[34:49]
	s_waitcnt lgkmcnt(0)
	s_barrier
	ds_read_b128 v[212:215], v182 offset:18432
	ds_read_b128 v[216:219], v162 offset:0
	ds_read_b128 v[220:223], v182 offset:23040
	ds_read_b128 v[224:227], v162 offset:4608
	ds_read_b128 v[228:231], v182 offset:18464
	ds_read_b128 v[232:235], v162 offset:32
	ds_read_b128 v[236:239], v182 offset:23072
	ds_read_b128 v[240:243], v162 offset:4640
	v_mfma_f32_32x32x16_bf16 v[18:33], v[184:187], v[196:199], v[18:33]
	v_mfma_f32_32x32x16_bf16 v[2:17], v[192:195], v[196:199], v[2:17]
	v_mfma_f32_32x32x16_bf16 v[50:65], v[200:203], v[204:207], v[50:65]
	v_mfma_f32_32x32x16_bf16 v[34:49], v[208:211], v[204:207], v[34:49]
	v_mfma_f32_32x32x16_bf16 v[18:33], v[200:203], v[248:251], v[18:33]
	v_mfma_f32_32x32x16_bf16 v[2:17], v[208:211], v[248:251], v[2:17]
	s_cbranch_vccz .LBB0_2265
.LBB0_2253:
	s_cmp_gt_u32 s13, 12
	s_waitcnt vmcnt(5)
	ds_write_b128 v160, v[66:69] offset:36864
	s_waitcnt vmcnt(4)
	ds_write_b128 v160, v[70:73] offset:55296
	s_waitcnt vmcnt(3)
	ds_write_b128 v160, v[74:77] offset:41472
	s_waitcnt vmcnt(2)
	ds_write_b128 v160, v[78:81] offset:59904
	s_waitcnt vmcnt(1)
	ds_write_b128 v160, v[82:85] offset:46080
	ds_write_b128 v160, v[86:89] offset:64512
	s_waitcnt vmcnt(0)
	ds_write_b128 v160, v[102:105] offset:50688
	ds_write_b128 v161, v[114:117] offset:13824
	s_cbranch_scc1 .LBB0_2259
	s_nop 0
	s_nop 0
	s_nop 0
	s_nop 0
	global_load_dwordx4 v[66:69], v158, s[84:85] offset:384
	s_nop 0
	global_load_dwordx4 v[70:73], v156, s[86:87] offset:384
	v_mov_b32_e32 v131, v130
	global_load_dwordx4 v[74:77], v154, s[84:85] offset:384
	v_mov_b64_e32 v[88:89], v[130:131]
	global_load_dwordx4 v[78:81], v152, s[86:87] offset:384
	v_mov_b64_e32 v[86:87], v[130:131]
	global_load_dwordx4 v[82:85], v150, s[84:85] offset:384
	s_and_saveexec_b64 s[2:3], s[6:7]
	s_cbranch_execz .LBB0_2256
	s_nop 1
	global_load_dwordx4 v[86:89], v148, s[86:87] offset:384
.LBB0_2256:
	s_or_b64 exec, exec, s[2:3]
	v_mov_b32_e32 v115, 0
	s_nop 0
	global_load_dwordx4 v[102:105], v146, s[84:85] offset:384
	v_mov_b32_e32 v114, 0
	v_mov_b32_e32 v117, 0
	v_mov_b32_e32 v116, 0
	s_and_saveexec_b64 s[2:3], s[8:9]
	s_cbranch_execz .LBB0_2258
	s_nop 1
	global_load_dwordx4 v[114:117], v144, s[86:87] offset:384

.LBB0_2259:
	s_cmp_gt_u32 s13, 13
	s_cselect_b64 s[2:3], -1, 0
	s_and_b64 vcc, exec, s[2:3]
	s_waitcnt lgkmcnt(4)
	v_mfma_f32_32x32x16_bf16 v[50:65], v[212:215], v[216:219], v[50:65]
	v_mfma_f32_32x32x16_bf16 v[34:49], v[220:223], v[216:219], v[34:49]
	v_mfma_f32_32x32x16_bf16 v[18:33], v[212:215], v[224:227], v[18:33]
	v_mfma_f32_32x32x16_bf16 v[2:17], v[220:223], v[224:227], v[2:17]
	ds_read_b128 v[184:187], v182 offset:18496
	ds_read_b128 v[188:191], v162 offset:64
	ds_read_b128 v[192:195], v182 offset:23104
	ds_read_b128 v[196:199], v162 offset:4672
	s_waitcnt lgkmcnt(4)
	v_mfma_f32_32x32x16_bf16 v[50:65], v[228:231], v[232:235], v[50:65]
	v_mfma_f32_32x32x16_bf16 v[34:49], v[236:239], v[232:235], v[34:49]
	v_mfma_f32_32x32x16_bf16 v[18:33], v[228:231], v[240:243], v[18:33]
	v_mfma_f32_32x32x16_bf16 v[2:17], v[236:239], v[240:243], v[2:17]
	ds_read_b128 v[200:203], v182 offset:18528
	ds_read_b128 v[204:207], v162 offset:96
	ds_read_b128 v[208:211], v182 offset:23136
	ds_read_b128 v[248:251], v162 offset:4704
	s_waitcnt lgkmcnt(4)
	v_mfma_f32_32x32x16_bf16 v[50:65], v[184:187], v[188:191], v[50:65]
	v_mfma_f32_32x32x16_bf16 v[34:49], v[192:195], v[188:191], v[34:49]
	s_waitcnt lgkmcnt(0)
	s_barrier
	ds_read_b128 v[212:215], v182 offset:55296
	ds_read_b128 v[216:219], v162 offset:36864
	ds_read_b128 v[220:223], v182 offset:59904
	ds_read_b128 v[224:227], v162 offset:41472
	ds_read_b128 v[228:231], v182 offset:55328
	ds_read_b128 v[232:235], v162 offset:36896
	ds_read_b128 v[236:239], v182 offset:59936
	ds_read_b128 v[240:243], v162 offset:41504
	v_mfma_f32_32x32x16_bf16 v[18:33], v[184:187], v[196:199], v[18:33]
	v_mfma_f32_32x32x16_bf16 v[2:17], v[192:195], v[196:199], v[2:17]
	v_mfma_f32_32x32x16_bf16 v[50:65], v[200:203], v[204:207], v[50:65]
	v_mfma_f32_32x32x16_bf16 v[34:49], v[208:211], v[204:207], v[34:49]
	v_mfma_f32_32x32x16_bf16 v[18:33], v[200:203], v[248:251], v[18:33]
	v_mfma_f32_32x32x16_bf16 v[2:17], v[208:211], v[248:251], v[2:17]
	s_cbranch_vccnz .LBB0_2252
	s_cmp_gt_u32 s13, 11
	s_waitcnt vmcnt(5)
	ds_write_b128 v160, v[90:93]
	s_waitcnt vmcnt(4)
	ds_write_b128 v160, v[94:97] offset:18432
	s_waitcnt vmcnt(3)
	ds_write_b128 v160, v[98:101] offset:4608
	s_waitcnt vmcnt(2)
	ds_write_b128 v160, v[106:109] offset:23040
	s_waitcnt vmcnt(1)
	ds_write_b128 v160, v[110:113] offset:9216
	ds_write_b128 v160, v[118:121] offset:27648
	s_waitcnt vmcnt(0)
	ds_write_b128 v160, v[122:125] offset:13824
	ds_write_b128 v160, v[126:129] offset:32256
	s_cbranch_scc1 .LBB0_2252
	s_nop 0
	s_nop 0
	s_nop 0
	s_nop 0
	global_load_dwordx4 v[90:93], v158, s[84:85] offset:512
	s_nop 0
	global_load_dwordx4 v[94:97], v156, s[86:87] offset:512
	v_mov_b32_e32 v131, v130
	global_load_dwordx4 v[98:101], v154, s[84:85] offset:512
	v_mov_b64_e32 v[120:121], v[130:131]
	global_load_dwordx4 v[106:109], v152, s[86:87] offset:512
	v_mov_b64_e32 v[118:119], v[130:131]
	global_load_dwordx4 v[110:113], v150, s[84:85] offset:512
	s_and_saveexec_b64 s[14:15], s[6:7]
	s_cbranch_execz .LBB0_2263
	s_nop 1
	global_load_dwordx4 v[118:121], v148, s[86:87] offset:512
.LBB0_2263:
	s_or_b64 exec, exec, s[14:15]
	v_mov_b32_e32 v127, 0
	s_nop 0
	global_load_dwordx4 v[122:125], v146, s[84:85] offset:512
	v_mov_b32_e32 v126, 0
	v_mov_b32_e32 v129, 0
	v_mov_b32_e32 v128, 0
	s_and_saveexec_b64 s[14:15], s[8:9]
	s_cbranch_execz .LBB0_2251
	s_nop 1
	global_load_dwordx4 v[126:129], v144, s[86:87] offset:512
	s_branch .LBB0_2251

.LBB0_2922:
	s_or_b64 exec, exec, s[20:21]
	v_add_u32_e32 v4, s35, v158
	v_ashrrev_i32_e32 v5, 31, v4
	v_lshlrev_b64 v[4:5], 12, v[4:5]
	v_lshl_add_u64 v[140:141], s[82:83], 0, v[4:5]
	v_add_u32_e32 v4, s35, v159
	v_ashrrev_i32_e32 v5, 31, v4
	v_lshlrev_b64 v[4:5], 12, v[4:5]
	v_lshl_add_u64 v[144:145], s[82:83], 0, v[4:5]
	v_add_u32_e32 v4, s35, v160
	v_ashrrev_i32_e32 v5, 31, v4
	v_lshlrev_b64 v[4:5], 12, v[4:5]
	v_lshl_add_u64 v[148:149], s[82:83], 0, v[4:5]
	v_add_u32_e32 v4, s35, v1
	v_ashrrev_i32_e32 v5, 31, v4
	v_lshlrev_b64 v[4:5], 12, v[4:5]
	v_lshl_add_u64 v[138:139], s[82:83], 0, v[48:49]
	v_lshl_add_u64 v[142:143], s[82:83], 0, v[42:43]
	v_lshl_add_u64 v[146:147], s[82:83], 0, v[36:37]
	v_lshl_add_u64 v[150:151], s[82:83], 0, v[34:35]
	v_lshl_add_u64 v[152:153], s[82:83], 0, v[4:5]
	s_mov_b32 s37, 0
	v_mov_b32_e32 v3, v2
	v_mov_b32_e32 v4, v2
	v_mov_b32_e32 v5, v2
	v_mov_b32_e32 v6, v2
	v_mov_b32_e32 v7, v2
	v_mov_b32_e32 v8, v2
	v_mov_b32_e32 v9, v2
	v_mov_b32_e32 v10, v2
	v_mov_b32_e32 v11, v2
	v_mov_b32_e32 v12, v2
	v_mov_b32_e32 v13, v2
	v_mov_b32_e32 v14, v2
	v_mov_b32_e32 v15, v2
	v_mov_b32_e32 v16, v2
	v_mov_b32_e32 v17, v2
	v_mov_b32_e32 v18, v2
	v_mov_b32_e32 v19, v2
	v_mov_b32_e32 v20, v2
	v_mov_b32_e32 v21, v2
	v_mov_b32_e32 v22, v2
	v_mov_b32_e32 v23, v2
	v_mov_b32_e32 v24, v2
	v_mov_b32_e32 v25, v2
	v_mov_b32_e32 v26, v2
	v_mov_b32_e32 v27, v2
	v_mov_b32_e32 v28, v2
	v_mov_b32_e32 v29, v2
	v_mov_b32_e32 v30, v2
	v_mov_b32_e32 v31, v2
	v_mov_b32_e32 v32, v2
	v_mov_b32_e32 v33, v2
	v_mov_b32_e32 v34, v2
	v_mov_b32_e32 v35, v2
	v_mov_b32_e32 v36, v2
	v_mov_b32_e32 v37, v2
	v_mov_b32_e32 v38, v2
	v_mov_b32_e32 v39, v2
	v_mov_b32_e32 v40, v2
	v_mov_b32_e32 v41, v2
	v_mov_b32_e32 v42, v2
	v_mov_b32_e32 v43, v2
	v_mov_b32_e32 v44, v2
	v_mov_b32_e32 v45, v2
	v_mov_b32_e32 v46, v2
	v_mov_b32_e32 v47, v2
	v_mov_b32_e32 v48, v2
	v_mov_b32_e32 v49, v2
	v_mov_b32_e32 v50, v2
	v_mov_b32_e32 v51, v2
	v_mov_b32_e32 v52, v2
	v_mov_b32_e32 v53, v2
	v_mov_b32_e32 v54, v2
	v_mov_b32_e32 v55, v2
	v_mov_b32_e32 v56, v2
	v_mov_b32_e32 v57, v2
	v_mov_b32_e32 v58, v2
	v_mov_b32_e32 v59, v2
	v_mov_b32_e32 v60, v2
	v_mov_b32_e32 v61, v2
	v_mov_b32_e32 v62, v2
	v_mov_b32_e32 v63, v2
	v_mov_b32_e32 v64, v2
	v_mov_b32_e32 v65, v2
	s_waitcnt lgkmcnt(0)
	s_barrier
	ds_read_b128 v[192:195], v161 offset:0
	ds_read_b128 v[196:199], v162 offset:18432
	ds_read_b128 v[200:203], v162 offset:23040
	ds_read_b128 v[204:207], v161 offset:4608
	ds_read_b128 v[208:211], v161 offset:32
	ds_read_b128 v[212:215], v162 offset:18464
	ds_read_b128 v[216:219], v162 offset:23072
	ds_read_b128 v[220:223], v161 offset:4640
	v_subrev_u32_e32 v152, s82, v152
	v_add_u32_e32 v152, v152, v136
	v_subrev_u32_e32 v150, s82, v150
	v_add_u32_e32 v150, v150, v136
	v_subrev_u32_e32 v148, s82, v148
	v_add_u32_e32 v148, v148, v136
	v_subrev_u32_e32 v146, s82, v146
	v_add_u32_e32 v146, v146, v136
	v_subrev_u32_e32 v144, s82, v144
	v_add_u32_e32 v144, v144, v136
	v_subrev_u32_e32 v142, s82, v142
	v_add_u32_e32 v142, v142, v136
	v_subrev_u32_e32 v140, s82, v140
	v_add_u32_e32 v140, v140, v136
	v_subrev_u32_e32 v138, s82, v138
	v_add_u32_e32 v138, v138, v136
	s_add_u32 s84, s82, 0x10740000
	s_addc_u32 s85, s83, 0
	s_add_u32 s86, s82, 0x95d0000
	s_addc_u32 s87, s83, 0
	s_branch .LBB0_2925

.LBB0_2925:
	s_cmp_gt_u32 s37, 28
	s_waitcnt vmcnt(3)
	ds_write_b128 v154, v[66:69] offset:36864
	ds_write_b128 v154, v[70:73] offset:55296
	s_waitcnt vmcnt(2)
	ds_write_b128 v154, v[78:81] offset:41472
	ds_write_b128 v154, v[74:77] offset:59904
	s_waitcnt vmcnt(1)
	ds_write_b128 v154, v[82:85] offset:46080
	ds_write_b128 v154, v[90:93] offset:64512
	s_waitcnt vmcnt(0)
	ds_write_b128 v154, v[102:105] offset:50688
	ds_write_b128 v156, v[106:109] offset:13824
	s_cbranch_scc1 .LBB0_2935
	v_mov_b32_e32 v76, 0
	s_nop 0
	global_load_dwordx4 v[66:69], v152, s[84:85] offset:384
	v_mov_b32_e32 v77, v130
	v_mov_b64_e32 v[72:73], v[76:77]
	v_mov_b64_e32 v[70:71], v[76:77]
	s_and_saveexec_b64 s[20:21], s[4:5]
	s_cbranch_execz .LBB0_2928
	s_nop 1
	global_load_dwordx4 v[70:73], v150, s[86:87] offset:384

.LBB0_2935:
	s_cmp_gt_u32 s37, 29
	s_cselect_b64 s[20:21], -1, 0
	s_and_b64 vcc, exec, s[20:21]
	s_waitcnt lgkmcnt(4)
	v_mfma_f32_32x32x16_bf16 v[50:65], v[192:195], v[196:199], v[50:65]
	v_mfma_f32_32x32x16_bf16 v[34:49], v[192:195], v[200:203], v[34:49]
	v_mfma_f32_32x32x16_bf16 v[18:33], v[204:207], v[196:199], v[18:33]
	v_mfma_f32_32x32x16_bf16 v[2:17], v[204:207], v[200:203], v[2:17]
	ds_read_b128 v[164:167], v161 offset:64
	ds_read_b128 v[168:171], v162 offset:18496
	ds_read_b128 v[172:175], v162 offset:23104
	ds_read_b128 v[176:179], v161 offset:4672
	s_waitcnt lgkmcnt(4)
	v_mfma_f32_32x32x16_bf16 v[50:65], v[208:211], v[212:215], v[50:65]
	v_mfma_f32_32x32x16_bf16 v[34:49], v[208:211], v[216:219], v[34:49]
	v_mfma_f32_32x32x16_bf16 v[18:33], v[220:223], v[212:215], v[18:33]
	v_mfma_f32_32x32x16_bf16 v[2:17], v[220:223], v[216:219], v[2:17]
	ds_read_b128 v[180:183], v161 offset:96
	ds_read_b128 v[184:187], v162 offset:18528
	ds_read_b128 v[188:191], v162 offset:23136
	ds_read_b128 v[224:227], v161 offset:4704
	s_waitcnt lgkmcnt(4)
	v_mfma_f32_32x32x16_bf16 v[50:65], v[164:167], v[168:171], v[50:65]
	v_mfma_f32_32x32x16_bf16 v[34:49], v[164:167], v[172:175], v[34:49]
	s_waitcnt lgkmcnt(0)
	s_barrier
	ds_read_b128 v[192:195], v161 offset:36864
	ds_read_b128 v[196:199], v162 offset:55296
	ds_read_b128 v[200:203], v162 offset:59904
	ds_read_b128 v[204:207], v161 offset:41472
	ds_read_b128 v[208:211], v161 offset:36896
	ds_read_b128 v[212:215], v162 offset:55328
	ds_read_b128 v[216:219], v162 offset:59936
	ds_read_b128 v[220:223], v161 offset:41504
	v_mfma_f32_32x32x16_bf16 v[18:33], v[176:179], v[168:171], v[18:33]
	v_mfma_f32_32x32x16_bf16 v[2:17], v[176:179], v[172:175], v[2:17]
	v_mfma_f32_32x32x16_bf16 v[50:65], v[180:183], v[184:187], v[50:65]
	v_mfma_f32_32x32x16_bf16 v[34:49], v[180:183], v[188:191], v[34:49]
	v_mfma_f32_32x32x16_bf16 v[18:33], v[224:227], v[184:187], v[18:33]
	v_mfma_f32_32x32x16_bf16 v[2:17], v[224:227], v[188:191], v[2:17]
	s_cbranch_vccnz .LBB0_2924
	s_cmp_gt_u32 s37, 27
	s_waitcnt vmcnt(3)
	ds_write_b128 v154, v[86:89]
	ds_write_b128 v154, v[94:97] offset:18432
	s_waitcnt vmcnt(2)
	ds_write_b128 v154, v[110:113] offset:4608
	ds_write_b128 v154, v[98:101] offset:23040
	s_waitcnt vmcnt(1)
	ds_write_b128 v154, v[114:117] offset:9216
	ds_write_b128 v154, v[118:121] offset:27648
	s_waitcnt vmcnt(0)
	ds_write_b128 v154, v[122:125] offset:13824
	ds_write_b128 v154, v[126:129] offset:32256
	s_cbranch_scc1 .LBB0_2924
	v_mov_b32_e32 v100, 0
	s_nop 0
	global_load_dwordx4 v[86:89], v152, s[84:85] offset:512
	v_mov_b32_e32 v101, v130
	v_mov_b64_e32 v[96:97], v[100:101]
	v_mov_b64_e32 v[94:95], v[100:101]
	s_and_saveexec_b64 s[22:23], s[4:5]
	s_cbranch_execz .LBB0_2939
	s_nop 1
	global_load_dwordx4 v[94:97], v150, s[86:87] offset:512

.LBB0_3121:
	s_or_b64 exec, exec, s[2:3]
	v_add_u32_e32 v2, s33, v194
	v_ashrrev_i32_e32 v3, 31, v2
	v_lshlrev_b64 v[2:3], 11, v[2:3]
	v_lshl_add_u64 v[168:169], s[82:83], 0, v[2:3]
	v_add_u32_e32 v2, s33, v195
	v_ashrrev_i32_e32 v3, 31, v2
	v_lshlrev_b64 v[2:3], 11, v[2:3]
	v_lshl_add_u64 v[172:173], s[82:83], 0, v[2:3]
	v_add_u32_e32 v2, s33, v196
	v_ashrrev_i32_e32 v3, 31, v2
	v_lshlrev_b64 v[2:3], 11, v[2:3]
	v_lshl_add_u64 v[176:177], s[82:83], 0, v[2:3]
	v_add_u32_e32 v2, s33, v1
	v_ashrrev_i32_e32 v3, 31, v2
	v_lshlrev_b64 v[2:3], 11, v[2:3]
	v_lshl_add_u64 v[166:167], s[82:83], 0, v[48:49]
	v_lshl_add_u64 v[170:171], s[82:83], 0, v[42:43]
	v_lshl_add_u64 v[174:175], s[82:83], 0, v[36:37]
	v_lshl_add_u64 v[178:179], s[82:83], 0, v[34:35]
	v_lshl_add_u64 v[180:181], s[82:83], 0, v[2:3]
	s_mov_b32 s35, 0
	v_mov_b32_e32 v51, v50
	v_mov_b32_e32 v52, v50
	v_mov_b32_e32 v53, v50
	v_mov_b32_e32 v54, v50
	v_mov_b32_e32 v55, v50
	v_mov_b32_e32 v56, v50
	v_mov_b32_e32 v57, v50
	v_mov_b32_e32 v58, v50
	v_mov_b32_e32 v59, v50
	v_mov_b32_e32 v60, v50
	v_mov_b32_e32 v61, v50
	v_mov_b32_e32 v62, v50
	v_mov_b32_e32 v63, v50
	v_mov_b32_e32 v64, v50
	v_mov_b32_e32 v65, v50
	v_mov_b32_e32 v34, v50
	v_mov_b32_e32 v35, v50
	v_mov_b32_e32 v36, v50
	v_mov_b32_e32 v37, v50
	v_mov_b32_e32 v38, v50
	v_mov_b32_e32 v39, v50
	v_mov_b32_e32 v40, v50
	v_mov_b32_e32 v41, v50
	v_mov_b32_e32 v42, v50
	v_mov_b32_e32 v43, v50
	v_mov_b32_e32 v44, v50
	v_mov_b32_e32 v45, v50
	v_mov_b32_e32 v46, v50
	v_mov_b32_e32 v47, v50
	v_mov_b32_e32 v48, v50
	v_mov_b32_e32 v49, v50
	v_mov_b32_e32 v18, v50
	v_mov_b32_e32 v19, v50
	v_mov_b32_e32 v20, v50
	v_mov_b32_e32 v21, v50
	v_mov_b32_e32 v22, v50
	v_mov_b32_e32 v23, v50
	v_mov_b32_e32 v24, v50
	v_mov_b32_e32 v25, v50
	v_mov_b32_e32 v26, v50
	v_mov_b32_e32 v27, v50
	v_mov_b32_e32 v28, v50
	v_mov_b32_e32 v29, v50
	v_mov_b32_e32 v30, v50
	v_mov_b32_e32 v31, v50
	v_mov_b32_e32 v32, v50
	v_mov_b32_e32 v33, v50
	v_mov_b32_e32 v2, v50
	v_mov_b32_e32 v3, v50
	v_mov_b32_e32 v4, v50
	v_mov_b32_e32 v5, v50
	v_mov_b32_e32 v6, v50
	v_mov_b32_e32 v7, v50
	v_mov_b32_e32 v8, v50
	v_mov_b32_e32 v9, v50
	v_mov_b32_e32 v10, v50
	v_mov_b32_e32 v11, v50
	v_mov_b32_e32 v12, v50
	v_mov_b32_e32 v13, v50
	v_mov_b32_e32 v14, v50
	v_mov_b32_e32 v15, v50
	v_mov_b32_e32 v16, v50
	v_mov_b32_e32 v17, v50
	s_waitcnt lgkmcnt(0)
	s_barrier
	ds_read_b128 v[206:209], v203 offset:0
	ds_read_b128 v[210:213], v204 offset:18432
	ds_read_b128 v[214:217], v204 offset:23040
	ds_read_b128 v[218:221], v203 offset:4608
	ds_read_b128 v[222:225], v203 offset:32
	ds_read_b128 v[226:229], v204 offset:18464
	ds_read_b128 v[230:233], v204 offset:23072
	ds_read_b128 v[234:237], v203 offset:4640
	v_subrev_u32_e32 v180, s82, v180
	v_add_u32_e32 v180, v180, v138
	v_subrev_u32_e32 v178, s82, v178
	v_add_u32_e32 v178, v178, v138
	v_subrev_u32_e32 v176, s82, v176
	v_add_u32_e32 v176, v176, v138
	v_subrev_u32_e32 v174, s82, v174
	v_add_u32_e32 v174, v174, v138
	v_subrev_u32_e32 v172, s82, v172
	v_add_u32_e32 v172, v172, v138
	v_subrev_u32_e32 v170, s82, v170
	v_add_u32_e32 v170, v170, v138
	v_subrev_u32_e32 v168, s82, v168
	v_add_u32_e32 v168, v168, v138
	v_subrev_u32_e32 v166, s82, v166
	v_add_u32_e32 v166, v166, v138
	s_add_u32 s84, s82, 0x149c0000
	s_addc_u32 s85, s83, 0
	s_add_u32 s86, s82, 0x9dd0000
	s_addc_u32 s87, s83, 0
	s_branch .LBB0_3124
